# phase 10: background weight conversion disabled (phase 12 drains it) to trim the phase tail; otherwise identical to previous best
# baseline (speedup 1.0000x reference)
; #define LAS __attribute__((address_space(3)))
; template <bool DRAIN>
; __device__ __forceinline__ void bg_convert(const float* wg1, const float* wu1, const float* wd1, unsigned char* wsw, unsigned* ctl, int done_word, int G, LAS float* scr, int lane) {
;     for (;;) {
;         if (!DRAIN) { if (__hip_atomic_load(ctl + done_word, __ATOMIC_RELAXED, __HIP_MEMORY_SCOPE_AGENT) >= (unsigned)G) break; }
;         int i0 = 0;
;         if (lane == 0) i0 = (int)atomicAdd(ctl + 896, 4u);
;         i0 = __builtin_amdgcn_readfirstlane(i0);
;         if (i0 >= BG_ITEMS) break;
;     ...
;             __syncthreads();
;             if (tid == 0) atomicAdd(ctl + 704, 1u);
;             bg_convert<false>(p.in[I_WG] + (size_t)DM * FFN, p.in[I_WU] + (size_t)DM * FFN, p.in[I_WD] + (size_t)DM * FFN, wsw, ctl, 704, G, scr, lane);
.LBB0_1159:
	s_or_b64 exec, exec, s[6:7]
	v_mov_b32_e32 v1, 0
	s_load_dwordx4 s[4:7], s[42:43], 0x78
	s_load_dwordx2 s[10:11], s[42:43], 0x88
	global_load_dword v0, v1, s[40:41] offset:2816 sc1
	s_waitcnt vmcnt(0)
	v_cmp_le_u32_e32 vcc, s34, v0
	s_cbranch_vccnz .LBB0_1178
	s_cmp_ge_u32 s33, 0
	s_cbranch_scc1 .LBB0_1178
	s_waitcnt lgkmcnt(0)
	s_add_u32 s8, s4, 0x2c00000
	s_addc_u32 s9, s5, 0
	v_and_b32_e32 v2, 7, v183
	s_add_u32 s6, s6, 0x2c00000
	v_lshrrev_b32_e32 v6, 3, v241
	v_lshlrev_b32_e32 v0, 4, v2
	s_mul_i32 s14, s33, 0x2100
	s_addc_u32 s7, s7, 0
	v_or_b32_e32 v11, s14, v0
	v_mul_u32_u24_e32 v12, 0x84, v6
	s_movk_i32 s12, 0x420
	v_mov_b32_e32 v3, s14
	v_lshl_add_u64 v[4:5], s[40:41], 0, v[0:1]
	s_mov_b64 s[14:15], 0x4c30000
	s_add_u32 s10, s10, 0x2c00000
	v_lshlrev_b32_e32 v26, 2, v2
	v_mad_u32_u24 v10, v2, s12, v3
	v_lshl_add_u64 v[2:3], v[4:5], 0, s[14:15]
	s_mov_b64 s[14:15], 0x2030000
	v_add_u32_e32 v11, v11, v12
	s_addc_u32 s11, s11, 0
	s_mov_b32 s13, 0
	v_cmp_eq_u32_e64 s[4:5], 0, v241
	v_or_b32_e32 v7, 8, v6
	v_or_b32_e32 v8, 16, v6
	v_or_b32_e32 v9, 24, v6
	v_lshl_or_b32 v10, v6, 2, v10
	v_lshl_add_u64 v[4:5], v[4:5], 0, s[14:15]
	s_mov_b32 s20, 0x10000
	s_mov_b32 s21, 0x20000
	s_mov_b32 s22, 0x30000
	s_mov_b32 s23, 0x40000
	s_mov_b32 s24, 0x50000
	s_mov_b32 s25, 0x60000
	s_mov_b32 s26, 0x70000
	v_add_u32_e32 v12, 0x420, v11
	v_add_u32_e32 v13, 0x428, v11
	v_add_u32_e32 v14, 0x840, v11
	v_add_u32_e32 v15, 0x848, v11
	v_add_u32_e32 v16, 0xc60, v11
	v_add_u32_e32 v17, 0xc68, v11
	v_add_u32_e32 v18, 0x1080, v11
	v_add_u32_e32 v19, 0x1088, v11
	v_add_u32_e32 v20, 0x14a0, v11
	v_add_u32_e32 v21, 0x14a8, v11
	v_add_u32_e32 v22, 0x18c0, v11
	v_add_u32_e32 v23, 0x18c8, v11
	v_add_u32_e32 v24, 0x1ce0, v11
	v_add_u32_e32 v25, 0x1ce8, v11
	s_mov_b32 s27, 0x2c000
	s_mov_b32 s42, 0x58000
	s_mov_b32 s43, 0x84000
	s_mov_b32 s44, 0xb0000
	s_mov_b32 s45, 0xdc000
	s_mov_b32 s46, 0x108000
	s_mov_b32 s47, 0x134000
	s_mov_b32 s48, 0x80000
	v_lshlrev_b32_e32 v0, 2, v26
	s_branch .LBB0_1163
